# mixer-C loop: K/V global prefetch of tile t+3 issued right after the staging stores of tile t+2 (one full iteration of latency slack instead of nine MFMA gaps)
# speedup vs baseline: 1.0056x; 1.0017x over previous
; __device__ __forceinline__ void attn_c_unit(LAS unsigned char* lds, const bf16_t* proj, const bf16_t* vt, bf16_t* obuf, int b, int hk, int blk, float mref, unsigned long long* sg) {
;     ...
;     const int qhead = 4 * hk + (w >> 1), qpos = blk * 128 + 64 * (w & 1) + r, qcol = QC_OFF + 64 * qhead, kcol = KC_OFF + 64 * hk, vslot = 10 + hk, ocol = 1024 + 64 * qhead;
;     const size_t tokbase = (size_t)b * SEQ;
;     const int srow = tid >> 3, sch = tid & 7;
;     const bf16_t* kg = proj + (tokbase + srow) * INW + kcol + sch * 8;
;     const bf16_t* vg = vt + ((size_t)(b * NVS + vslot) * 64 + srow) * SEQ + sch * 8;
;     const unsigned sdst = srow * KP + sch * 16;
;     u32x4 kreg, vreg;
;     const bf16_t* qg = proj + (tokbase + qpos) * INW + qcol + 8 * h;
;     bf16x8 qf[2][4];
; #pragma unroll
;     for (int j = 0; j < 2; ++j)
; #pragma unroll
;         for (int ks = 0; ks < 4; ++ks) qf[j][ks] = *(const bf16x8*)(qg + (size_t)(32 * j) * INW + 16 * ks);
;     f32x16 negm;
; #pragma unroll
;     for (int i = 0; i < 16; ++i) negm[i] = 0.f;
;     float l0 = 0.f, l1 = 0.f;
;     f32x16 o00, o01, o10, o11;
; #pragma unroll
;     for (int i = 0; i < 16; ++i) { o00[i] = 0.f; o01[i] = 0.f; o10[i] = 0.f; o11[i] = 0.f; }
;     const int pr = (r & ~12) | ((r & 4) << 1) | ((r & 8) >> 1);
;     constexpr int nT = SEQ / 64;
;     constexpr int CK = 0, CV = 4 * ATT_TILE;
; #pragma unroll
;     for (int i = 0; i < 2; ++i) { kreg = *(const u32x4*)(kg + (size_t)(i * 64) * INW); vreg = *(const u32x4*)(vg + i * 64);
;         *(LAS u32x4*)(lds + CK + i * ATT_TILE + sdst) = kreg; *(LAS u32x4*)(lds + CV + i * ATT_TILE + sdst) = vreg; }
;     __syncthreads();
;     for (int it = 0; it < nT; ++it) {
;         const int buf = it & 3;
;         if (it + 2 < nT) { kreg = *(const u32x4*)(kg + (size_t)((it + 2) * 64) * INW); vreg = *(const u32x4*)(vg + (it + 2) * 64); }
;         const LAS unsigned char* kb = lds + CK + buf * ATT_TILE + pr * KP + 16 * h;
;         f32x16 s00, s01, s10, s11;
;         {
;             const bf16x8 a0 = *(const LAS bf16x8*)(kb), a1 = *(const LAS bf16x8*)(kb + 32 * KP);
;             s00 = __builtin_amdgcn_mfma_f32_32x32x16_bf16(a0, qf[0][0], negm, 0, 0, 0);
;             s10 = __builtin_amdgcn_mfma_f32_32x32x16_bf16(a0, qf[1][0], negm, 0, 0, 0);
;             s01 = __builtin_amdgcn_mfma_f32_32x32x16_bf16(a1, qf[0][0], negm, 0, 0, 0);
.LBB0_207:
	s_bfe_u32 s24, s11, 0x10002
	v_mov_b32_e32 v18, v199
	s_lshl_b32 s54, s24, 13
	v_ashrrev_i32_e32 v8, 3, v18
	v_add_u32_e32 v0, s54, v8
	v_mov_b64_e32 v[10:11], s[86:87]
	s_and_b32 s22, s11, 3
	s_waitcnt lgkmcnt(0)
	v_mad_i64_i32 v[0:1], s[12:13], v0, s25, v[10:11]
	s_mul_i32 s14, s24, 14
	s_lshl_b32 s12, s22, 7
	s_mov_b32 s13, s55
	v_lshlrev_b32_e32 v4, 4, v18
	s_add_i32 s15, s22, s14
	v_lshl_add_u64 v[0:1], v[0:1], 0, s[12:13]
	v_and_b32_e32 v128, 0x70, v4
	s_lshl_b32 s12, s15, 6
	v_lshl_add_u64 v[14:15], v[0:1], 0, v[128:129]
	v_ashrrev_i32_e32 v9, 31, v8
	s_addk_i32 s12, 0x280
	v_add_co_u32_e32 v0, vcc, s48, v14
	v_lshl_add_u64 v[2:3], s[12:13], 0, v[8:9]
	s_nop 0
	v_addc_co_u32_e32 v1, vcc, 0, v15, vcc
	s_mov_b32 s12, 0x79000
	v_add_co_u32_e32 v14, vcc, s12, v14
	s_and_b32 s12, s10, 3
	s_add_i32 s14, s14, s12
	s_lshl_b32 s13, s14, 6
	s_add_i32 s14, s13, 0x280
	s_lshl_b32 s26, s12, 7
	v_readfirstlane_b32 s12, v18
	s_lshl_b32 s13, s11, 4
	s_and_b32 s13, s13, 0xffffff80
	s_and_b32 s23, s12, 64
	v_and_b32_e32 v19, 31, v18
	s_or_b32 s13, s13, s23
	v_lshlrev_b64 v[2:3], 14, v[2:3]
	v_or_b32_e32 v182, s13, v19
	v_lshl_add_u64 v[2:3], s[84:85], 0, v[2:3]
	v_addc_co_u32_e32 v15, vcc, 0, v15, vcc
	s_ashr_i32 s12, s12, 1
	v_ashrrev_i32_e32 v183, 31, v182
	v_lshl_add_u64 v[12:13], v[2:3], 0, v[128:129]
	global_load_dwordx4 v[0:3], v[0:1], off offset:2560
	s_nop 0
	global_load_dwordx4 v[4:7], v[12:13], off
	global_load_dwordx4 v[130:133], v[14:15], off offset:2560
	global_load_dwordx4 v[134:137], v[12:13], off offset:128
	s_lshl_b32 s13, s22, 8
	s_andn2_b32 s12, s12, 63
	v_lshl_add_u64 v[184:185], v[182:183], 0, s[54:55]
	s_add_i32 s12, s12, s13
	v_mad_u64_u32 v[10:11], s[22:23], v184, s25, v[10:11]
	v_bfe_u32 v196, v18, 5, 1
	v_mad_i32_i24 v11, v185, s25, v11
	s_ashr_i32 s13, s12, 31
	v_lshl_add_u64 v[10:11], s[12:13], 1, v[10:11]
	v_lshlrev_b32_e32 v12, 4, v196
	v_mov_b32_e32 v13, v129
	v_lshl_add_u64 v[10:11], v[10:11], 0, v[12:13]
	s_mov_b64 s[22:23], 0x1200
	v_add_co_u32_e32 v16, vcc, s48, v10
	v_lshl_add_u64 v[14:15], v[10:11], 0, s[22:23]
	s_nop 0
	v_addc_co_u32_e32 v17, vcc, 0, v11, vcc
	s_mov_b32 s23, 0x3d000
	v_add_co_u32_e32 v10, vcc, s23, v10
	global_load_dwordx4 v[138:141], v[14:15], off offset:32
	global_load_dwordx4 v[142:145], v[14:15], off offset:64
	global_load_dwordx4 v[146:149], v[16:17], off offset:512
	global_load_dwordx4 v[150:153], v[14:15], off offset:96
	v_addc_co_u32_e32 v11, vcc, 0, v11, vcc
	global_load_dwordx4 v[154:157], v[10:11], off offset:512
	global_load_dwordx4 v[158:161], v[10:11], off offset:544
	global_load_dwordx4 v[162:165], v[10:11], off offset:576
	global_load_dwordx4 v[166:169], v[10:11], off offset:608
	v_mul_lo_u32 v10, v8, s16
	v_lshlrev_b32_e32 v11, 1, v18
	v_lshrrev_b32_e32 v13, 1, v18
	v_add3_u32 v197, v10, v128, 0
	v_and_b32_e32 v11, 8, v11
	v_and_b32_e32 v13, 4, v13
	s_mov_b32 s15, s55
	v_mov_b32_e32 v32, 0
	s_mov_b32 s22, 0
	v_mov_b32_e32 v33, v32
	v_mov_b32_e32 v34, v32
	v_mov_b32_e32 v35, v32
	v_mov_b32_e32 v36, v32
	v_mov_b32_e32 v37, v32
	v_mov_b32_e32 v38, v32
	s_waitcnt vmcnt(11)
	ds_write_b128 v197, v[0:3]
	s_waitcnt vmcnt(10)
	ds_write_b128 v197, v[4:7] offset:36864
	s_waitcnt vmcnt(9)
	ds_write_b128 v197, v[130:133] offset:9216
	s_waitcnt vmcnt(8)
	ds_write_b128 v197, v[134:137] offset:46080
	v_and_b32_e32 v0, 19, v18
	v_or3_b32 v0, v0, v11, v13
	v_mul_u32_u24_e32 v0, 0x90, v0
	v_add3_u32 v198, 0, v0, v12
	v_mul_u32_u24_e32 v0, 0x90, v19
	v_add3_u32 v200, 0, v0, v12
	v_lshl_add_u64 v[0:1], v[8:9], 0, s[14:15]
	v_lshlrev_b64 v[0:1], 14, v[0:1]
	v_or_b32_e32 v0, v0, v128
	v_lshl_add_u64 v[186:187], s[4:5], 0, v[0:1]
	v_mad_i64_i32 v[0:1], s[14:15], v8, s25, 0
	v_mad_u64_u32 v[0:1], s[14:15], s24, v222, v[0:1]
	v_or3_b32 v0, v0, s26, v128
	v_lshl_add_u64 v[188:189], s[6:7], 0, v[0:1]
	v_mov_b32_e32 v39, v32
	v_mov_b32_e32 v40, v32
	v_mov_b32_e32 v41, v32
	v_mov_b32_e32 v42, v32
	v_mov_b32_e32 v43, v32
	v_mov_b32_e32 v44, v32
	v_mov_b32_e32 v45, v32
	v_mov_b32_e32 v46, v32
	v_mov_b32_e32 v47, v32
	v_mov_b32_e32 v48, v32
	v_mov_b32_e32 v49, v32
	v_mov_b32_e32 v50, v32
	v_mov_b32_e32 v51, v32
	v_mov_b32_e32 v52, v32
	v_mov_b32_e32 v53, v32
	v_mov_b32_e32 v54, v32
	v_mov_b32_e32 v55, v32
	v_mov_b32_e32 v56, v32
	v_mov_b32_e32 v57, v32
	v_mov_b32_e32 v58, v32
	v_mov_b32_e32 v59, v32
	v_mov_b32_e32 v60, v32
	v_mov_b32_e32 v61, v32
	v_mov_b32_e32 v62, v32
	v_mov_b32_e32 v63, v32
	v_mov_b32_e32 v0, v32
	v_mov_b32_e32 v1, v32
	v_mov_b32_e32 v2, v32
	v_mov_b32_e32 v3, v32
	v_mov_b32_e32 v4, v32
	v_mov_b32_e32 v5, v32
	v_mov_b32_e32 v6, v32
	v_mov_b32_e32 v7, v32
	v_mov_b32_e32 v8, v32
	v_mov_b32_e32 v9, v32
	v_mov_b32_e32 v10, v32
	v_mov_b32_e32 v11, v32
	v_mov_b32_e32 v12, v32
	v_mov_b32_e32 v13, v32
	v_mov_b32_e32 v14, v32
	v_mov_b32_e32 v15, v32
	v_mov_b32_e32 v16, v32
	v_mov_b32_e32 v17, v32
	v_mov_b32_e32 v18, v32
	v_mov_b32_e32 v19, v32
	v_mov_b32_e32 v20, v32
	v_mov_b32_e32 v21, v32
	v_mov_b32_e32 v22, v32
	v_mov_b32_e32 v23, v32
	v_mov_b32_e32 v24, v32
	v_mov_b32_e32 v25, v32
	v_mov_b32_e32 v26, v32
	v_mov_b32_e32 v27, v32
	v_mov_b32_e32 v28, v32
	v_mov_b32_e32 v29, v32
	v_mov_b32_e32 v30, v32
	v_mov_b32_e32 v31, v32
	v_mov_b32_e32 v190, v32
	v_mov_b32_e32 v191, v32
	s_waitcnt vmcnt(0) lgkmcnt(0)
	s_barrier
	ds_read_b128 v[226:229], v198 offset:0
	ds_read_b128 v[230:233], v198 offset:32
	ds_read_b128 v[234:237], v198 offset:64
	ds_read_b128 v[238:241], v198 offset:96
	ds_read_b128 v[202:205], v200 offset:36928
	ds_read_b128 v[192:195], v200 offset:41536
	ds_read_b128 v[210:213], v200 offset:36960
	ds_read_b128 v[242:245], v200 offset:41568
	v_mov_b32_e32 v214, 0
	v_mov_b32_e32 v215, 0
	v_mov_b32_e32 v96, 0
	v_mov_b32_e32 v97, 0
	v_mov_b32_e32 v98, 0
	v_mov_b32_e32 v99, 0
	v_mov_b32_e32 v100, 0
	v_mov_b32_e32 v101, 0
	v_mov_b32_e32 v102, 0
	v_mov_b32_e32 v103, 0
	v_mov_b32_e32 v112, 0
	v_mov_b32_e32 v113, 0
	v_mov_b32_e32 v114, 0
	v_mov_b32_e32 v115, 0
	v_mov_b32_e32 v116, 0
	v_mov_b32_e32 v117, 0
	v_mov_b32_e32 v118, 0
	v_mov_b32_e32 v119, 0
	v_mov_b32_e32 v128, v198
	s_waitcnt lgkmcnt(4)
	v_mfma_f32_32x32x16_bf16 v[64:79], v[226:229], v[146:149], 0
	v_mfma_f32_32x32x16_bf16 v[64:79], v[230:233], v[138:141], v[64:79]
	v_mfma_f32_32x32x16_bf16 v[64:79], v[234:237], v[142:145], v[64:79]
	v_mfma_f32_32x32x16_bf16 v[64:79], v[238:241], v[150:153], v[64:79]
	v_mfma_f32_32x32x16_bf16 v[80:95], v[238:241], v[166:169], 0
	ds_read_b128 v[238:241], v128 offset:4704
	v_mfma_f32_32x32x16_bf16 v[80:95], v[234:237], v[162:165], v[80:95]
	ds_read_b128 v[234:237], v128 offset:4672
	v_mfma_f32_32x32x16_bf16 v[80:95], v[230:233], v[158:161], v[80:95]
	ds_read_b128 v[230:233], v128 offset:4640
	v_mfma_f32_32x32x16_bf16 v[80:95], v[226:229], v[154:157], v[80:95]
	ds_read_b128 v[226:229], v128 offset:4608
	global_load_dwordx4 v[130:133], v[188:189], off
	global_load_dwordx4 v[134:137], v[186:187], off
	s_nop 7
; #define LAS __attribute__((address_space(3)))
; __device__ __forceinline__ void attn_c_unit(LAS unsigned char* lds, const bf16_t* proj, const bf16_t* vt, bf16_t* obuf, int b, int hk, int blk, float mref, unsigned long long* sg) {
;     ...
;         if (it + 2 < nT) { kreg = *(const u32x4*)(kg + (size_t)((it + 2) * 64) * INW); vreg = *(const u32x4*)(vg + (it + 2) * 64); }
;         const LAS unsigned char* kb = lds + CK + buf * ATT_TILE + pr * KP + 16 * h;
;         f32x16 s00, s01, s10, s11;
;         {
;             const bf16x8 a0 = *(const LAS bf16x8*)(kb), a1 = *(const LAS bf16x8*)(kb + 32 * KP);
;             s00 = __builtin_amdgcn_mfma_f32_32x32x16_bf16(a0, qf[0][0], negm, 0, 0, 0);
;             s10 = __builtin_amdgcn_mfma_f32_32x32x16_bf16(a0, qf[1][0], negm, 0, 0, 0);
;             s01 = __builtin_amdgcn_mfma_f32_32x32x16_bf16(a1, qf[0][0], negm, 0, 0, 0);
;             s11 = __builtin_amdgcn_mfma_f32_32x32x16_bf16(a1, qf[1][0], negm, 0, 0, 0);
;         }
; #pragma unroll
;         for (int ks = 1; ks < 4; ++ks) {
;             const bf16x8 a0 = *(const LAS bf16x8*)(kb + 32 * ks), a1 = *(const LAS bf16x8*)(kb + 32 * KP + 32 * ks);
;             s00 = __builtin_amdgcn_mfma_f32_32x32x16_bf16(a0, qf[0][ks], s00, 0, 0, 0);
;             s10 = __builtin_amdgcn_mfma_f32_32x32x16_bf16(a0, qf[1][ks], s10, 0, 0, 0);
;             s01 = __builtin_amdgcn_mfma_f32_32x32x16_bf16(a1, qf[0][ks], s01, 0, 0, 0);
;             s11 = __builtin_amdgcn_mfma_f32_32x32x16_bf16(a1, qf[1][ks], s11, 0, 0, 0);
;         }
;         u32x4 pw0[4], pw1[4];
;         {
;             float ps = 0.f;
; #pragma unroll
;             for (int i = 0; i < 16; ++i) { s00[i] = __builtin_amdgcn_exp2f(s00[i]); s01[i] = __builtin_amdgcn_exp2f(s01[i]); ps += s00[i] + s01[i]; }
;             l0 += ps;
; #pragma unroll
;             for (int q = 0; q < 4; ++q) { pw0[0][q] = pk_bf16(s00[2 * q], s00[2 * q + 1]); pw0[1][q] = pk_bf16(s00[8 + 2 * q], s00[8 + 2 * q + 1]);
;                                           pw0[2][q] = pk_bf16(s01[2 * q], s01[2 * q + 1]); pw0[3][q] = pk_bf16(s01[8 + 2 * q], s01[8 + 2 * q + 1]); }
;         }
;         {
;             float ps = 0.f;
; #pragma unroll
;             for (int i = 0; i < 16; ++i) { s10[i] = __builtin_amdgcn_exp2f(s10[i]); s11[i] = __builtin_amdgcn_exp2f(s11[i]); ps += s10[i] + s11[i]; }
;             l1 += ps;
; #pragma unroll
.Lc_top:
	s_waitcnt lgkmcnt(4)
	v_mfma_f32_32x32x16_bf16 v[32:47], v[202:205], v[96:99], v[32:47]
	v_exp_f32_e32 v64, v64
	v_exp_f32_e32 v65, v65
	v_exp_f32_e32 v66, v66
	v_exp_f32_e32 v67, v67
	v_add_f32_e32 v190, v190, v64
	v_mfma_f32_32x32x16_bf16 v[32:47], v[210:213], v[100:103], v[32:47]
	s_and_b32 s24, s22, 7
	s_mulk_i32 s24, 0x2400
	v_add_f32_e32 v214, v214, v65
	v_cvt_pk_bf16_f32 v64, v64, v65
	v_exp_f32_e32 v68, v68
	v_exp_f32_e32 v69, v69
	v_add_f32_e32 v190, v190, v66
	v_mfma_f32_32x32x16_bf16 v[0:15], v[210:213], v[116:119], v[0:15]
	v_add_u32_e32 v246, s24, v200
	v_add_f32_e32 v214, v214, v67
	v_cvt_pk_bf16_f32 v65, v66, v67
	v_exp_f32_e32 v70, v70
	v_exp_f32_e32 v71, v71
	v_add_f32_e32 v190, v190, v68
	v_mfma_f32_32x32x16_bf16 v[0:15], v[202:205], v[112:115], v[0:15]
	v_lshl_add_u64 v[186:187], v[186:187], 0, s[64:65]
	v_add_f32_e32 v214, v214, v69
	v_cvt_pk_bf16_f32 v66, v68, v69
	v_exp_f32_e32 v72, v72
	v_exp_f32_e32 v73, v73
	v_add_f32_e32 v190, v190, v70
	v_mfma_f32_32x32x16_bf16 v[16:31], v[192:195], v[112:115], v[16:31]
	v_lshl_add_u64 v[188:189], v[188:189], 0, s[68:69]
	v_add_f32_e32 v214, v214, v71
	v_cvt_pk_bf16_f32 v67, v70, v71
	v_exp_f32_e32 v74, v74
	v_exp_f32_e32 v75, v75
	v_add_f32_e32 v190, v190, v72
	v_mfma_f32_32x32x16_bf16 v[16:31], v[242:245], v[116:119], v[16:31]
	s_and_b32 s23, s22, 3
	s_mulk_i32 s23, 0x2400
	s_xor_b32 s23, s23, 0x4800
	v_add_f32_e32 v214, v214, v73
	v_cvt_pk_bf16_f32 v68, v72, v73
	v_exp_f32_e32 v76, v76
	v_exp_f32_e32 v77, v77
	v_add_f32_e32 v190, v190, v74
	v_mfma_f32_32x32x16_bf16 v[48:63], v[242:245], v[100:103], v[48:63]
	v_add_u32_e32 v201, s23, v197
	s_add_i32 s23, s22, 2
	s_and_b32 s23, s23, 7
	s_mulk_i32 s23, 0x2400
	v_add_f32_e32 v214, v214, v75
	v_cvt_pk_bf16_f32 v69, v74, v75
	v_exp_f32_e32 v78, v78
	v_exp_f32_e32 v79, v79
	v_add_f32_e32 v190, v190, v76
	v_mfma_f32_32x32x16_bf16 v[48:63], v[192:195], v[96:99], v[48:63]
	ds_read_b128 v[202:205], v246 offset:36864
	ds_read_b128 v[192:195], v246 offset:41472
	ds_read_b128 v[210:213], v246 offset:36896
	ds_read_b128 v[242:245], v246 offset:41504
	s_waitcnt lgkmcnt(4)
	v_add_f32_e32 v214, v214, v77
	v_cvt_pk_bf16_f32 v70, v76, v77
	v_add_f32_e32 v190, v190, v78
	v_add_f32_e32 v214, v214, v79
	v_cvt_pk_bf16_f32 v71, v78, v79
	v_mfma_f32_32x32x16_bf16 v[96:111], v[226:229], v[146:149], 0
	v_add_u32_e32 v206, s23, v197
	v_exp_f32_e32 v80, v80
	v_exp_f32_e32 v81, v81
	v_exp_f32_e32 v82, v82
	v_exp_f32_e32 v83, v83
	v_add_f32_e32 v191, v191, v80
	v_mfma_f32_32x32x16_bf16 v[96:111], v[230:233], v[138:141], v[96:111]
	s_cmpk_gt_u32 s22, 0x7d
	s_cbranch_scc1 .Lc_nostore
	s_waitcnt vmcnt(0)
	ds_write_b128 v201, v[130:133]
	ds_write_b128 v206, v[134:137] offset:36864
.Lc_nostore:
	s_cmpk_gt_u32 s22, 0x7c
	s_cbranch_scc1 .Lc_noload
	global_load_dwordx4 v[130:133], v[188:189], off
	global_load_dwordx4 v[134:137], v[186:187], off
